# sample attention: all 8 heads of a batch row mapped to one XCD (remap2) on top of v46
# baseline (speedup 1.0000x reference)
; __device__ __forceinline__ void attn_sample_item(const P& p, int wi, int lane) {
;     ...
;     const int bs = wi >> 5, i = (wi >> 3) & 3, h = wi & 7;
;     const int kg = lane >> 4, li = lane & 15;
;     const int srow = bs * 4 + i;
; __global__ void __launch_bounds__(NTHR) fwd_megakernel(P p) {
;     ...
;           if (w < 4) { for (int wi = w * G + blockIdx.x; wi < 1024; wi += G * 4) attn_sample_item(p, wi, t0 & 63); }
.LBB0_453:
	s_andn2_b64 vcc, exec, s[0:1]
	s_cbranch_vccnz .LBB0_479
	s_mul_i32 s0, s3, s34
	s_add_i32 s3, s0, s2
	s_cmpk_gt_i32 s3, 0x3ff
	s_cbranch_scc1 .LBB0_479
	s_lshl_b32 s77, s34, 2
	s_add_u32 s26, s68, 0x6200000
	s_addc_u32 s27, s69, 0
	s_add_u32 s28, s68, 0x6280000
	s_addc_u32 s29, s69, 0
	s_add_u32 s30, s70, 0x183a6400
	s_addc_u32 s31, s71, 0
	s_cmpk_lg_i32 s34, 0x100
	s_cbranch_scc1 .Las_item
	s_lshr_b32 s14, s3, 8
	s_lshl_b32 s14, s14, 3
	s_bfe_u32 s15, s2, 0x30003
	s_or_b32 s14, s14, s15
	s_and_b32 s15, s2, 7
	s_lshr_b32 s16, s2, 6
	s_lshl_b32 s16, s16, 3
	s_or_b32 s15, s15, s16
	s_lshl_b32 s15, s15, 5
	s_or_b32 s3, s14, s15
